# v16 plus GEMM phase prologues: second staging batch issued before the first wait (vmcnt(2)+barrier moved behind it as vmcnt(8))
# baseline (speedup 1.0000x reference)
; #define PG8_STAGE(bufoff, gbase, voff) do { _Pragma("unroll") for (int _i = 0; _i < 2; ++_i) \
;         __builtin_amdgcn_global_load_lds((const unsigned*)((const char*)(gbase) + (voff)[_i]), (PG8_LAS unsigned*)(lds + (bufoff) + ldsw + _i * 8192), 16, 0, 0); } while (0)
; #define PG8_WAIT_V(n) asm volatile("s_waitcnt vmcnt(" #n ")" ::: "memory")
; #define PG8_BAR __builtin_amdgcn_s_barrier()
; template <class Epi, class Sched, bool ALIGN_EPI = false, bool SP2 = false>
; __device__ __forceinline__ void gemm_phase(PG8_LAS unsigned char* lds, const Gemm g, const Sched& S, const Epi& E) {
;     ...
;     if constexpr (SP2) {
;         PG8_STAGE(PG8_SB(0, 0), cB, voffB); PG8_STAGE(PG8_SB(0, 1), cB + hstep, voffB); PG8_STAGE(PG8_SA(0, 0), cA, voffA); PG8_STAGE(PG8_SA(0, 1), cA + hstep, voffA);
;         if (wr == 1) PG8_BAR;
;         PG8_WAIT_V(2); PG8_BAR;
;         PG8_STAGE(PG8_SB(1, 0), cB + kstep, voffB); PG8_STAGE(PG8_SA(1, 0), cA + kstep, voffA); PG8_STAGE(PG8_SB(1, 1), cB + hstep + kstep, voffB);
;         PG8_WAIT_V(6); PG8_BAR;
.LBB0_263:
	v_lshrrev_b32_e32 v16, 1, v14
	v_and_b32_e32 v16, 24, v16
	s_sext_i32_i16 s12, s18
	s_waitcnt lgkmcnt(0)
	s_add_u32 s18, s4, 0x1756c000
	v_and_b32_e32 v15, 15, v14
	v_lshlrev_b32_e32 v17, 1, v16
	v_lshlrev_b32_e32 v14, 2, v14
	s_addc_u32 s19, s5, 0
	v_lshl_or_b32 v162, s21, 6, v15
	v_lshl_or_b32 v15, v15, 6, v17
	s_lshl_b32 s4, s21, 13
	v_and_b32_e32 v14, 32, v14
	v_bitop3_b32 v17, v15, s4, v14 bitop3:0xde
	s_lshl_b32 s4, s20, 5
	s_and_b32 s37, s4, 0x60
	s_add_i32 m0, s25, 0x18000
	v_lshl_add_u64 v[6:7], v[6:7], 0, s[30:31]
	s_lshl_b32 s4, s37, 7
	global_load_lds_dwordx4 v[6:7], off
	v_lshl_add_u64 v[4:5], v[4:5], 0, s[30:31]
	s_add_i32 m0, s25, 0x1a000
	s_add_i32 s33, s25, 0x8000
	s_add_i32 s35, s25, 0xa000
	v_bitop3_b32 v163, v15, s4, v14 bitop3:0xde
	global_load_lds_dwordx4 v[4:5], off
	v_lshl_add_u64 v[0:1], v[0:1], 0, s[30:31]
	s_mov_b32 m0, s33
	s_add_u32 s4, s52, 0x40080
	global_load_lds_dwordx4 v[0:1], off
	v_lshl_add_u64 v[0:1], v[2:3], 0, s[30:31]
	s_mov_b32 m0, s35
	s_addc_u32 s5, s53, 0
	global_load_lds_dwordx4 v[0:1], off
	s_add_i32 m0, s25, 0x1c000
	v_lshl_add_u64 v[0:1], s[4:5], 0, v[128:129]
	global_load_lds_dwordx4 v[0:1], off
	v_lshl_add_u64 v[0:1], s[4:5], 0, v[146:147]
	s_add_i32 m0, s25, 0x1e000
	s_cmpk_lt_u32 s17, 0x100
	global_load_lds_dwordx4 v[0:1], off
	v_lshlrev_b32_e32 v0, 14, v12
	v_and_b32_e32 v0, 0xffff8000, v0
	v_lshl_add_u32 v0, v11, 11, v0
	v_and_b32_e32 v1, 1, v12
	v_lshl_or_b32 v0, v1, 6, v0
	v_lshl_add_u32 v152, v13, 1, v0
	v_lshlrev_b32_e32 v0, 14, v8
	v_and_b32_e32 v0, 0xffff8000, v0
	s_waitcnt vmcnt(8)
	s_barrier
	s_waitcnt vmcnt(6)
	v_lshl_add_u32 v0, v9, 11, v0
	v_and_b32_e32 v1, 1, v8
	v_lshl_or_b32 v0, v1, 6, v0
	s_cselect_b64 s[20:21], -1, 0
	v_or_b32_e32 v164, s37, v16
	v_mov_b32_e32 v153, v129
	v_lshl_add_u32 v154, v10, 1, v0
	v_mov_b32_e32 v155, v129
	s_mov_b32 s37, 0
	v_add_u32_e32 v165, 0, v17
	s_barrier
	s_branch .LBB0_266

; #define PG8_STAGE(bufoff, gbase, voff) do { _Pragma("unroll") for (int _i = 0; _i < 2; ++_i) \
;         __builtin_amdgcn_global_load_lds((const unsigned*)((const char*)(gbase) + (voff)[_i]), (PG8_LAS unsigned*)(lds + (bufoff) + ldsw + _i * 8192), 16, 0, 0); } while (0)
; #define PG8_WAIT_V(n) asm volatile("s_waitcnt vmcnt(" #n ")" ::: "memory")
; #define PG8_BAR __builtin_amdgcn_s_barrier()
;     __host__ __device__ bool next(int i, Unit& u) const {
;         u.kt0 = 0; u.nkt = nkt; u.sliced = 0; u.ha = -1; u.hb = -1;
;         if (mode == 0 || i < rounds) { const long L = (long)i * G + c; if (L >= nwg) return false; tile((int)L, u); return true; }
;         if (i > rounds || c >= left * mode) return false;
;         int t, piece;
;         if ((left & 7) == 0) { const int q = c >> 3, x = c & 7; t = x + 8 * (q / mode); piece = q % mode; } else { t = c / mode; piece = c % mode; }
;         tile(rounds * G + t, u); u.ha = piece & 1; u.hb = (mode == 4) ? (piece >> 1) : -1; return true;
; template <class Epi, class Sched, bool ALIGN_EPI = false, bool SP2 = false>
; __device__ __forceinline__ void gemm_phase(PG8_LAS unsigned char* lds, const Gemm g, const Sched& S, const Epi& E) {
;     ...
;     if constexpr (SP2) {
;         PG8_STAGE(PG8_SB(0, 0), cB, voffB); PG8_STAGE(PG8_SB(0, 1), cB + hstep, voffB); PG8_STAGE(PG8_SA(0, 0), cA, voffA); PG8_STAGE(PG8_SA(0, 1), cA + hstep, voffA);
;         if (wr == 1) PG8_BAR;
;         PG8_WAIT_V(2); PG8_BAR;
;         PG8_STAGE(PG8_SB(1, 0), cB + kstep, voffB); PG8_STAGE(PG8_SA(1, 0), cA + kstep, voffA); PG8_STAGE(PG8_SB(1, 1), cB + hstep + kstep, voffB);
;         PG8_WAIT_V(6); PG8_BAR;
.LBB0_352:
	v_lshrrev_b32_e32 v16, 1, v8
	v_and_b32_e32 v16, 24, v16
	s_waitcnt lgkmcnt(0)
	s_add_u32 s58, s52, 0x1756c000
	v_and_b32_e32 v15, 15, v8
	v_lshlrev_b32_e32 v17, 1, v16
	v_lshlrev_b32_e32 v8, 2, v8
	s_addc_u32 s59, s53, 0
	v_lshl_or_b32 v211, s17, 6, v15
	v_lshl_or_b32 v15, v15, 6, v17
	s_lshl_b32 s17, s17, 13
	v_and_b32_e32 v8, 32, v8
	v_bitop3_b32 v17, v15, s17, v8 bitop3:0xde
	s_lshl_b32 s17, s33, 5
	s_and_b32 s17, s17, 0x60
	s_lshl_b32 s33, s17, 7
	v_bitop3_b32 v8, v15, s33, v8 bitop3:0xde
	s_add_i32 s33, s16, 0x18000
	v_lshl_add_u64 v[6:7], v[6:7], 0, s[30:31]
	s_mov_b32 m0, s33
	s_add_i32 s35, s16, 0x1a000
	global_load_lds_dwordx4 v[6:7], off
	v_lshl_add_u64 v[4:5], v[4:5], 0, s[30:31]
	s_mov_b32 m0, s35
	s_add_i32 s37, s16, 0x8000
	s_add_i32 s38, s16, 0xa000
	global_load_lds_dwordx4 v[4:5], off
	v_lshl_add_u64 v[0:1], v[0:1], 0, s[30:31]
	s_mov_b32 m0, s37
	s_add_u32 s50, s6, 0x40080
	global_load_lds_dwordx4 v[0:1], off
	v_lshl_add_u64 v[0:1], v[2:3], 0, s[30:31]
	s_mov_b32 m0, s38
	s_addc_u32 s51, s7, 0
	s_add_i32 s39, s16, 0x1c000
	global_load_lds_dwordx4 v[0:1], off
	v_lshl_add_u64 v[0:1], s[50:51], 0, v[204:205]
	s_mov_b32 m0, s39
	v_or_b32_e32 v213, s17, v16
	global_load_lds_dwordx4 v[0:1], off
	v_lshl_add_u64 v[0:1], s[50:51], 0, v[208:209]
	s_add_i32 s50, s16, 0x1e000
	s_mov_b32 m0, s50
	s_cmpk_lt_u32 s12, 0x100
	global_load_lds_dwordx4 v[0:1], off
	v_cvt_f32_ubyte0_e32 v0, s2
	v_rcp_iflag_f32_e32 v0, v0
	v_readlane_b32 s12, v255, 8
	s_mul_i32 s12, s2, s12
	v_readlane_b32 s17, v254, 0
	v_mul_f32_e32 v0, 0x4f7ffffe, v0
	v_cvt_u32_f32_e32 v0, v0
	s_cselect_b64 s[62:63], -1, 0
	s_cmp_lt_i32 s17, s12
	s_cselect_b64 s[64:65], -1, 0
	s_cmp_eq_u32 s2, 4
	s_cselect_b64 s[68:69], -1, 0
	s_sub_i32 s12, 0, s2
	v_readfirstlane_b32 s17, v0
	s_mul_i32 s12, s12, s17
	s_mul_hi_u32 s12, s17, s12
	s_add_i32 s17, s17, s12
	v_readlane_b32 s52, v254, 23
	s_mul_hi_u32 s12, s52, s17
	s_mul_i32 s51, s12, s2
	s_sub_i32 s51, s52, s51
	s_add_i32 s52, s12, 1
	s_sub_i32 s53, s51, s2
	s_cmp_ge_u32 s51, s2
	s_cselect_b32 s12, s52, s12
	s_cselect_b32 s51, s53, s51
	s_add_i32 s52, s12, 1
	s_cmp_ge_u32 s51, s2
	s_cselect_b32 s12, s52, s12
	v_readlane_b32 s56, v254, 7
	s_xor_b32 s12, s12, s56
	v_readlane_b32 s52, v254, 24
	s_sub_i32 s54, s12, s56
	s_mul_hi_u32 s12, s52, s17
	s_mul_i32 s17, s12, s2
	s_sub_i32 s17, s52, s17
	s_add_i32 s52, s12, 1
	s_sub_i32 s53, s17, s2
	s_cmp_ge_u32 s17, s2
	v_lshlrev_b32_e32 v0, 14, v9
	s_cselect_b32 s12, s52, s12
	v_and_b32_e32 v0, 0xffff8000, v0
	s_cselect_b32 s55, s53, s17
	s_add_i32 s17, s12, 1
	v_lshl_add_u32 v0, v10, 11, v0
	v_and_b32_e32 v1, 1, v9
	s_cmp_ge_u32 s55, s2
	v_lshl_or_b32 v0, v1, 6, v0
	s_cselect_b32 s12, s17, s12
	v_lshl_add_u32 v214, v11, 1, v0
	v_lshlrev_b32_e32 v0, 14, v12
	s_xor_b32 s12, s12, s56
	v_and_b32_e32 v0, 0xffff8000, v0
	s_waitcnt vmcnt(8)
	s_barrier
	s_waitcnt vmcnt(6)
	s_sub_i32 s12, s12, s56
	v_lshl_add_u32 v0, v13, 11, v0
	v_and_b32_e32 v1, 1, v12
	s_lshl_b32 s12, s12, 3
	v_readlane_b32 s17, v254, 32
	v_lshl_or_b32 v0, v1, 6, v0
	s_mov_b32 s61, 0
	s_or_b32 s56, s12, s17
	v_mov_b32_e32 v215, v129
	v_lshl_add_u32 v216, v14, 1, v0
	v_mov_b32_e32 v217, v129
	v_add_u32_e32 v228, 0, v8
	v_add_u32_e32 v229, 0, v17
	s_barrier
	s_branch .LBB0_355

; #define PG8_STAGE(bufoff, gbase, voff) do { _Pragma("unroll") for (int _i = 0; _i < 2; ++_i) \
;         __builtin_amdgcn_global_load_lds((const unsigned*)((const char*)(gbase) + (voff)[_i]), (PG8_LAS unsigned*)(lds + (bufoff) + ldsw + _i * 8192), 16, 0, 0); } while (0)
; #define PG8_WAIT_V(n) asm volatile("s_waitcnt vmcnt(" #n ")" ::: "memory")
; #define PG8_BAR __builtin_amdgcn_s_barrier()
;     __host__ __device__ bool next(int i, Unit& u) const {
;         u.kt0 = 0; u.nkt = nkt; u.sliced = 0; u.ha = -1; u.hb = -1;
;         if (mode == 0 || i < rounds) { const long L = (long)i * G + c; if (L >= nwg) return false; tile((int)L, u); return true; }
;         if (i > rounds || c >= left * mode) return false;
;         int t, piece;
;         if ((left & 7) == 0) { const int q = c >> 3, x = c & 7; t = x + 8 * (q / mode); piece = q % mode; } else { t = c / mode; piece = c % mode; }
;         tile(rounds * G + t, u); u.ha = piece & 1; u.hb = (mode == 4) ? (piece >> 1) : -1; return true;
; template <class Epi, class Sched, bool ALIGN_EPI = false, bool SP2 = false>
; __device__ __forceinline__ void gemm_phase(PG8_LAS unsigned char* lds, const Gemm g, const Sched& S, const Epi& E) {
;     ...
;     if constexpr (SP2) {
;         PG8_STAGE(PG8_SB(0, 0), cB, voffB); PG8_STAGE(PG8_SB(0, 1), cB + hstep, voffB); PG8_STAGE(PG8_SA(0, 0), cA, voffA); PG8_STAGE(PG8_SA(0, 1), cA + hstep, voffA);
;         if (wr == 1) PG8_BAR;
;         PG8_WAIT_V(2); PG8_BAR;
;         PG8_STAGE(PG8_SB(1, 0), cB + kstep, voffB); PG8_STAGE(PG8_SA(1, 0), cA + kstep, voffA); PG8_STAGE(PG8_SB(1, 1), cB + hstep + kstep, voffB);
;         PG8_WAIT_V(6); PG8_BAR;
.LBB0_414:
	s_waitcnt lgkmcnt(0)
	s_add_u32 s58, s52, 0x1756c000
	s_addc_u32 s59, s53, 0
	s_lshl_b32 s33, s33, 5
	s_and_b32 s57, s33, 0x60
	s_add_i32 s33, s16, 0x18000
	v_lshl_add_u64 v[6:7], v[6:7], 0, s[30:31]
	s_mov_b32 m0, s33
	s_add_i32 s35, s16, 0x1a000
	s_lshl_b32 s54, s51, 13
	s_lshl_b32 s55, s57, 7
	global_load_lds_dwordx4 v[6:7], off
	v_lshl_add_u64 v[4:5], v[4:5], 0, s[30:31]
	s_mov_b32 m0, s35
	s_add_i32 s37, s16, 0x8000
	s_add_i32 s38, s16, 0xa000
	global_load_lds_dwordx4 v[4:5], off
	v_lshl_add_u64 v[0:1], v[0:1], 0, s[30:31]
	s_mov_b32 m0, s37
	s_add_u32 s52, s6, 0x40080
	global_load_lds_dwordx4 v[0:1], off
	v_lshl_add_u64 v[0:1], v[2:3], 0, s[30:31]
	s_mov_b32 m0, s38
	s_addc_u32 s53, s7, 0
	s_add_i32 s39, s16, 0x1c000
	global_load_lds_dwordx4 v[0:1], off
	v_lshl_add_u64 v[0:1], s[52:53], 0, v[216:217]
	s_mov_b32 m0, s39
	s_add_i32 s50, s16, 0x1e000
	global_load_lds_dwordx4 v[0:1], off
	v_lshl_add_u64 v[0:1], s[52:53], 0, v[220:221]
	s_mov_b32 m0, s50
	s_cmpk_lt_u32 s12, 0x100
	global_load_lds_dwordx4 v[0:1], off
	v_lshrrev_b32_e32 v0, 1, v8
	v_and_b32_e32 v0, 24, v0
	v_and_b32_e32 v1, 15, v8
	v_lshlrev_b32_e32 v2, 1, v0
	v_lshl_or_b32 v211, s51, 6, v1
	v_lshl_or_b32 v1, v1, 6, v2
	v_lshlrev_b32_e32 v2, 2, v8
	v_and_b32_e32 v2, 32, v2
	v_bitop3_b32 v3, v1, s54, v2 bitop3:0xde
	v_bitop3_b32 v1, v1, s55, v2 bitop3:0xde
	v_cvt_f32_ubyte0_e32 v2, s2
	v_rcp_iflag_f32_e32 v2, v2
	v_readlane_b32 s12, v254, 0
	s_cselect_b64 s[62:63], -1, 0
	s_cmp_lt_i32 s12, s17
	v_mul_f32_e32 v2, 0x4f7ffffe, v2
	v_cvt_u32_f32_e32 v2, v2
	s_cselect_b64 s[64:65], -1, 0
	s_cmp_eq_u32 s2, 4
	s_cselect_b64 s[68:69], -1, 0
	s_sub_i32 s17, 0, s2
	v_readfirstlane_b32 s51, v2
	s_mul_i32 s17, s17, s51
	s_mul_hi_u32 s17, s51, s17
	s_add_i32 s17, s51, s17
	v_readlane_b32 s53, v254, 23
	s_mul_hi_u32 s51, s53, s17
	s_mul_i32 s52, s51, s2
	s_sub_i32 s52, s53, s52
	s_add_i32 s53, s51, 1
	s_sub_i32 s54, s52, s2
	s_cmp_ge_u32 s52, s2
	s_cselect_b32 s53, s53, s51
	s_cselect_b32 s51, s54, s52
	s_add_i32 s52, s53, 1
	s_cmp_ge_u32 s51, s2
	s_cselect_b32 s52, s52, s53
	v_readlane_b32 s56, v254, 7
	v_readlane_b32 s53, v254, 24
	s_xor_b32 s52, s52, s56
	s_mul_hi_u32 s17, s53, s17
	s_sub_i32 s54, s52, s56
	s_mul_i32 s52, s17, s2
	s_sub_i32 s52, s53, s52
	s_add_i32 s53, s17, 1
	s_sub_i32 s55, s52, s2
	s_cmp_ge_u32 s52, s2
	v_lshlrev_b32_e32 v2, 14, v9
	s_cselect_b32 s17, s53, s17
	v_and_b32_e32 v2, 0xffff8000, v2
	s_cselect_b32 s55, s55, s52
	s_add_i32 s52, s17, 1
	v_lshl_add_u32 v2, v10, 11, v2
	v_and_b32_e32 v4, 1, v9
	s_cmp_ge_u32 s55, s2
	v_lshl_or_b32 v2, v4, 6, v2
	s_cselect_b32 s17, s52, s17
	v_lshl_add_u32 v222, v11, 1, v2
	v_lshlrev_b32_e32 v2, 14, v12
	s_xor_b32 s17, s17, s56
	v_and_b32_e32 v2, 0xffff8000, v2
	s_waitcnt vmcnt(8)
	s_barrier
	s_waitcnt vmcnt(6)
	s_sub_i32 s17, s17, s56
	v_lshl_add_u32 v2, v13, 11, v2
	v_and_b32_e32 v4, 1, v12
	s_lshl_b32 s17, s17, 3
	v_readlane_b32 s52, v254, 32
	v_lshl_or_b32 v2, v4, 6, v2
	v_or_b32_e32 v213, s57, v0
	s_mov_b32 s12, 0
	s_or_b32 s56, s17, s52
	v_mov_b32_e32 v223, v129
	v_lshl_add_u32 v224, v14, 1, v2
	v_mov_b32_e32 v225, v129
	s_lshl_b32 s57, s57, 2
	v_lshlrev_b32_e32 v246, 2, v0
	v_add_u32_e32 v247, 0, v1
	v_add_u32_e32 v248, 0, v3
	s_barrier
	s_branch .LBB0_417

; #define PG8_STAGE(bufoff, gbase, voff) do { _Pragma("unroll") for (int _i = 0; _i < 2; ++_i) \
;         __builtin_amdgcn_global_load_lds((const unsigned*)((const char*)(gbase) + (voff)[_i]), (PG8_LAS unsigned*)(lds + (bufoff) + ldsw + _i * 8192), 16, 0, 0); } while (0)
; #define PG8_WAIT_V(n) asm volatile("s_waitcnt vmcnt(" #n ")" ::: "memory")
; #define PG8_BAR __builtin_amdgcn_s_barrier()
; #define KARG(name) ((decltype(Args::name))karg_ptr(offsetof(Args, name)))
; template <class Epi, class Sched, bool ALIGN_EPI = false, bool SP2 = false>
; __device__ __forceinline__ void gemm_phase(PG8_LAS unsigned char* lds, const Gemm g, const Sched& S, const Epi& E) {
;     ...
;     if constexpr (SP2) {
;         PG8_STAGE(PG8_SB(0, 0), cB, voffB); PG8_STAGE(PG8_SB(0, 1), cB + hstep, voffB); PG8_STAGE(PG8_SA(0, 0), cA, voffA); PG8_STAGE(PG8_SA(0, 1), cA + hstep, voffA);
;         if (wr == 1) PG8_BAR;
;         PG8_WAIT_V(2); PG8_BAR;
;         PG8_STAGE(PG8_SB(1, 0), cB + kstep, voffB); PG8_STAGE(PG8_SA(1, 0), cA + kstep, voffA); PG8_STAGE(PG8_SB(1, 1), cB + hstep + kstep, voffB);
;         PG8_WAIT_V(6); PG8_BAR;
; __global__ void __launch_bounds__(NTHREADS, 2) fwd_megakernel(Args a) {
;     ...
;             { pg8::Gemm g{A2, B2, M, DM, K2}; pg8::TailOrder S; S.init(M, DM, K2, F.G, (int)blockIdx.x, (layer == 3 && sub >= 1) ? 1 : 0);
;               const int sn = sl + 1, ln = sn / 3, subn = sn - ln * 3; const bool fold = sn < 12;
;               unsigned char* wsp = KARG(ws); const int snc = fold ? sn : 0, lnc = fold ? ln : 0;
;               float* e_x = (float*)(wsp + WS_XRES); bf16* e_xs = fold ? (bf16*)(wsp + WS_XN) : (bf16*)nullptr; const float* e_gn = KARG(norm_g) + (size_t)snc * 1024;
;               const float* e_scn = (const float*)(wsp + WS_MOD) + lnc * NMOD + (subn * 3 + 1) * 1024; float* e_rssn = (float*)(wsp + WS_RSS) + (size_t)snc * M;
;               const pg8::EpiRes E{e_x, gate, sub != 1 ? 1 : 0, e_xs, e_gn, e_scn, e_rssn};
.LBB0_829:
	s_add_i32 s16, s29, 1
	s_mul_hi_u32 s18, s16, 0xaaaaaaab
	s_lshr_b32 s20, s18, 1
	s_mul_i32 s18, s20, 0x3ffffd
	s_add_i32 s26, s18, s16
	s_cmp_lt_u32 s29, 11
	s_cselect_b64 s[92:93], -1, 0
	s_waitcnt lgkmcnt(0)
	s_add_u32 s94, s4, 0xa96c000
	s_addc_u32 s95, s5, 0
	s_add_u32 s96, s4, 0x1316c000
	s_addc_u32 s97, s5, 0
	v_readlane_b32 s52, v254, 17
	s_cmp_gt_u32 s29, 10
	v_readlane_b32 s53, v254, 18
	s_cselect_b32 s18, 0, s16
	s_mov_b32 s19, s53
	s_mulk_i32 s20, 0x2400
	s_cselect_b32 s22, 0, s20
	s_lshl_b64 s[20:21], s[18:19], 12
	s_add_u32 s20, s6, s20
	s_mov_b32 s23, s53
	s_addc_u32 s21, s7, s21
	s_lshl_b64 s[6:7], s[22:23], 2
	s_add_u32 s16, s4, s6
	s_mul_i32 s6, s26, 0xc00
	s_addc_u32 s19, s5, s7
	s_addk_i32 s6, 0x400
	s_ashr_i32 s7, s6, 31
	s_lshl_b64 s[6:7], s[6:7], 2
	s_add_u32 s6, s16, s6
	s_addc_u32 s7, s19, s7
	s_add_u32 s29, s6, 0x4000
	s_addc_u32 s22, s7, 0
	s_mul_i32 s7, s18, 0x22000
	s_mul_hi_u32 s6, s18, 0x22000
	s_add_u32 s4, s4, s7
	s_addc_u32 s5, s5, s6
	v_bfe_u32 v19, v12, 4, 2
	s_add_u32 s18, s4, 0x2856c000
	v_and_b32_e32 v211, 15, v12
	v_lshlrev_b32_e32 v20, 4, v19
	v_lshlrev_b32_e32 v12, 2, v12
	s_addc_u32 s19, s5, 0
	s_lshl_b32 s23, s0, 6
	v_lshl_or_b32 v20, v211, 6, v20
	s_lshl_b32 s0, s0, 13
	v_and_b32_e32 v12, 32, v12
	v_bitop3_b32 v21, v20, s0, v12 bitop3:0xde
	s_lshl_b32 s0, s1, 5
	s_and_b32 s6, s0, 0x60
	s_lshl_b32 s0, s6, 7
	v_bitop3_b32 v12, v20, s0, v12 bitop3:0xde
	s_lshr_b32 s3, s3, 6
	v_readlane_b32 s0, v255, 15
	v_readlane_b32 s1, v255, 16
	s_add_u32 s4, s78, s0
	v_readlane_b32 s0, v255, 20
	s_addc_u32 s5, s79, s1
	s_mulk_i32 s0, 0xc00
	s_mov_b32 s1, s53
	s_lshl_b64 s[0:1], s[0:1], 2
	s_add_u32 s0, s4, s0
	s_addc_u32 s1, s5, s1
	s_add_u32 s28, s0, 0x6000
	s_addc_u32 s26, s1, 0
	s_add_i32 s54, s50, 0x18000
	v_lshl_add_u64 v[0:1], v[0:1], 0, s[30:31]
	s_mov_b32 m0, s54
	s_add_i32 s1, s50, 0x1a000
	global_load_lds_dwordx4 v[0:1], off
	v_lshl_add_u64 v[0:1], v[2:3], 0, s[30:31]
	s_mov_b32 m0, s1
	s_add_i32 s0, s50, 0x8000
	global_load_lds_dwordx4 v[0:1], off
	v_lshl_add_u64 v[0:1], v[8:9], 0, s[30:31]
	s_mov_b32 m0, s0
	s_add_i32 s27, s50, 0xa000
	global_load_lds_dwordx4 v[0:1], off
	v_lshl_add_u64 v[0:1], v[10:11], 0, s[30:31]
	s_mov_b32 m0, s27
	s_add_i32 s16, s50, 0x1c000
	global_load_lds_dwordx4 v[0:1], off
	v_lshl_add_u64 v[0:1], v[4:5], 0, s[30:31]
	s_mov_b32 m0, s16
	s_add_i32 s38, s50, 0x1e000
	global_load_lds_dwordx4 v[0:1], off
	v_lshl_add_u64 v[0:1], v[6:7], 0, s[30:31]
	s_mov_b32 m0, s38
	s_cmpk_lt_u32 s17, 0x100
	global_load_lds_dwordx4 v[0:1], off
	v_cvt_f32_ubyte0_e32 v0, s56
	v_rcp_iflag_f32_e32 v0, v0
	s_cselect_b64 s[78:79], -1, 0
	v_lshl_or_b32 v233, v19, 3, s6
	s_add_i32 s55, s3, -2
	v_readlane_b32 s6, v254, 0
	s_cmp_lt_i32 s6, s24
	s_cselect_b64 s[58:59], -1, 0
	s_and_b32 s6, s12, 7
	s_cmp_lg_u32 s6, 0
	v_mul_f32_e32 v0, 0x4f7ffffe, v0
	s_cselect_b64 s[6:7], -1, 0
	s_lshr_b32 s37, s39, 1
	v_cvt_u32_f32_e32 v0, v0
	v_writelane_b32 v255, s6, 24
	s_cmp_eq_u32 s56, 4
	v_readlane_b32 s17, v254, 23
	v_writelane_b32 v255, s7, 25
	s_cselect_b64 s[6:7], -1, 0
	v_writelane_b32 v255, s6, 26
	s_waitcnt vmcnt(8)
	s_barrier
	s_waitcnt vmcnt(6)
	v_or_b32_e32 v213, s23, v211
	v_cndmask_b32_e64 v202, 0.5, 1.0, s[76:77]
	v_writelane_b32 v255, s7, 27
	s_sub_i32 s6, 0, s56
	v_readfirstlane_b32 s7, v0
	s_mul_i32 s6, s6, s7
	s_mul_hi_u32 s6, s7, s6
	s_add_i32 s7, s7, s6
	s_mul_hi_u32 s6, s17, s7
	s_mul_i32 s12, s6, s56
	s_sub_i32 s12, s17, s12
	s_add_i32 s17, s6, 1
	s_sub_i32 s24, s12, s56
	s_cmp_ge_u32 s12, s56
	s_cselect_b32 s6, s17, s6
	s_cselect_b32 s17, s24, s12
	s_add_i32 s12, s6, 1
	s_cmp_ge_u32 s17, s56
	s_cselect_b32 s6, s12, s6
	v_readlane_b32 s24, v254, 7
	s_xor_b32 s6, s6, s24
	v_writelane_b32 v255, s17, 28
	s_sub_i32 s6, s6, s24
	v_readlane_b32 s12, v254, 24
	v_writelane_b32 v255, s6, 29
	s_mul_hi_u32 s6, s12, s7
	s_mul_i32 s7, s6, s56
	s_sub_i32 s7, s12, s7
	s_add_i32 s12, s6, 1
	s_sub_i32 s17, s7, s56
	s_cmp_ge_u32 s7, s56
	s_cselect_b32 s6, s12, s6
	s_cselect_b32 s12, s17, s7
	s_add_i32 s7, s6, 1
	s_cmp_ge_u32 s12, s56
	s_cselect_b32 s6, s7, s6
	s_xor_b32 s6, s6, s24
	s_sub_i32 s6, s6, s24
	v_add_u32_e32 v0, v15, v13
	s_lshl_b32 s6, s6, 3
	v_add_lshl_u32 v128, v0, v14, 1
	v_add_u32_e32 v0, v18, v16
	v_writelane_b32 v255, s12, 30
	s_or_b32 s6, s6, s68
	v_lshl_add_u64 v[206:207], s[88:89], 0, v[128:129]
	v_add_lshl_u32 v128, v0, v17, 1
	s_mov_b32 s25, 0
	v_cmp_eq_u32_e64 s[4:5], 0, v19
	v_or_b32_e32 v226, 16, v213
	v_or_b32_e32 v227, 32, v213
	v_or_b32_e32 v228, 48, v213
	v_add_u32_e32 v229, 0x80, v213
	v_add_u32_e32 v230, 0x90, v213
	v_add_u32_e32 v231, 0xa0, v213
	v_add_u32_e32 v232, 0xb0, v213
	v_mov_b32_e32 v204, v202
	v_mov_b32_e32 v205, v202
	v_writelane_b32 v255, s6, 31
	v_lshl_add_u64 v[208:209], s[88:89], 0, v[128:129]
	v_add_u32_e32 v234, 0, v12
	v_add_u32_e32 v235, 0, v21
	s_barrier
	s_branch .LBB0_832
